# KV-compression GEMM: loads streamed double-buffered behind counted vmcnt; compressed-branch PV V fragments prefetched once per unit
# speedup vs baseline: 1.0443x; 1.0089x over previous
; #define MFMA16(a, b, c) __builtin_amdgcn_mfma_f32_16x16x32_f16((a), (b), (c), 0, 0, 0)
; DI void attn_phase(const Params& p, const int layer, const int wid_s) {
;     ...
;         f32x4 o[4];
; #pragma unroll
;         for (int dt = 0; dt < 4; ++dt) o[dt] = (f32x4){0.f, 0.f, 0.f, 0.f};
; #pragma unroll
;         for (int st = 0; st < 4; ++st) {
;           if (2 * st * 256 > t0 - 16) continue;
;           const half8 pf = {(h16)s[2 * st][0], (h16)s[2 * st][1], (h16)s[2 * st][2], (h16)s[2 * st][3],
;                             (h16)s[2 * st + 1][0], (h16)s[2 * st + 1][1], (h16)s[2 * st + 1][2], (h16)s[2 * st + 1][3]};
; #pragma unroll
;           for (int dt = 0; dt < 4; ++dt) {
;             const half8 vf = *(const half8*)(vcb + ((st * 64) + dt * 16 + fr) * 32 + fq * 8);
;             o[dt] = MFMA16(vf, pf, o[dt]);
;           }
;         }
.LBB0_266:
	v_lshl_add_u64 v[104:105], v[142:143], 0, s[10:11]
	v_lshlrev_b32_e32 v246, 1, v148
	v_add_co_u32_e32 v246, vcc, v104, v246
	s_nop 1
	v_addc_co_u32_e32 v247, vcc, 0, v105, vcc
	v_add_co_u32_e32 v246, vcc, 0x2000, v246
	s_nop 1
	v_addc_co_u32_e32 v247, vcc, 0, v247, vcc
	v_add_co_u32_e32 v254, vcc, 0x1000, v246
	s_nop 1
	v_addc_co_u32_e32 v255, vcc, 0, v247, vcc
	global_load_dwordx4 v[198:201], v[246:247], off offset:-4096
	global_load_dwordx4 v[202:205], v[246:247], off offset:-3072
	global_load_dwordx4 v[206:209], v[246:247], off offset:-2048
	global_load_dwordx4 v[210:213], v[246:247], off offset:-1024
	global_load_dwordx4 v[214:217], v[246:247], off
	global_load_dwordx4 v[218:221], v[246:247], off offset:1024
	global_load_dwordx4 v[222:225], v[246:247], off offset:2048
	global_load_dwordx4 v[226:229], v[246:247], off offset:3072
	global_load_dwordx4 v[230:233], v[254:255], off
	global_load_dwordx4 v[234:237], v[254:255], off offset:1024
	global_load_dwordx4 v[238:241], v[254:255], off offset:2048
	global_load_dwordx4 v[242:245], v[254:255], off offset:3072
	s_and_b64 vcc, exec, s[40:41]
	v_lshlrev_b32_e32 v106, 1, v148
	s_cbranch_vccnz .LBB0_286
	v_mov_b32_e32 v107, v1
	v_lshl_add_u64 v[98:99], v[104:105], 0, v[106:107]
	flat_load_dwordx4 v[90:93], v[98:99]
	flat_load_dwordx4 v[94:97], v[98:99] offset:1024
	v_cvt_pk_f16_f32 v193, v88, v89
	v_cvt_pk_f16_f32 v192, v2, v3
	v_cvt_pk_f16_f32 v191, v134, v135
	v_cvt_pk_f16_f32 v190, v152, v153
	flat_load_dwordx4 v[194:197], v[98:99] offset:3072
	s_waitcnt vmcnt(0) lgkmcnt(0)
	v_mfma_f32_16x16x32_f16 v[100:103], v[90:93], v[190:193], 0
	flat_load_dwordx4 v[88:91], v[98:99] offset:2048
	v_mfma_f32_16x16x32_f16 v[92:95], v[94:97], v[190:193], 0
	s_waitcnt vmcnt(0) lgkmcnt(0)
	v_mfma_f32_16x16x32_f16 v[96:99], v[88:91], v[190:193], 0
	v_mfma_f32_16x16x32_f16 v[88:91], v[194:197], v[190:193], 0
	s_and_b64 vcc, exec, s[42:43]
	s_cbranch_vccnz .LBB0_269
.LBB0_268:
	v_mov_b32_e32 v107, v1
	v_lshl_add_u64 v[2:3], v[104:105], 0, v[106:107]
	v_add_co_u32_e32 v2, vcc, 0x1000, v2
	v_cvt_pk_f16_f32 v134, v132, v133
	s_nop 0
	v_addc_co_u32_e32 v3, vcc, 0, v3, vcc
	v_cvt_pk_f16_f32 v133, v126, v127
	v_cvt_pk_f16_f32 v132, v128, v129
	v_cvt_pk_f16_f32 v135, v130, v131
	s_waitcnt vmcnt(0) lgkmcnt(0)
	s_nop 0
	v_mfma_f32_16x16x32_f16 v[100:103], v[198:201], v[132:135], v[100:103]
	v_mfma_f32_16x16x32_f16 v[92:95], v[202:205], v[132:135], v[92:95]
	v_mfma_f32_16x16x32_f16 v[96:99], v[206:209], v[132:135], v[96:99]
	v_mfma_f32_16x16x32_f16 v[88:91], v[210:213], v[132:135], v[88:91]

; #define MFMA16(a, b, c) __builtin_amdgcn_mfma_f32_16x16x32_f16((a), (b), (c), 0, 0, 0)
; DI void attn_phase(const Params& p, const int layer, const int wid_s) {
;     ...
;         for (int st = 0; st < 4; ++st) {
;           if (2 * st * 256 > t0 - 16) continue;
;           const half8 pf = {(h16)s[2 * st][0], (h16)s[2 * st][1], (h16)s[2 * st][2], (h16)s[2 * st][3],
;                             (h16)s[2 * st + 1][0], (h16)s[2 * st + 1][1], (h16)s[2 * st + 1][2], (h16)s[2 * st + 1][3]};
; #pragma unroll
;           for (int dt = 0; dt < 4; ++dt) {
;             const half8 vf = *(const half8*)(vcb + ((st * 64) + dt * 16 + fr) * 32 + fq * 8);
;             o[dt] = MFMA16(vf, pf, o[dt]);
;           }
.LBB0_271:
	v_mov_b32_e32 v107, v1
	v_lshl_add_u64 v[2:3], v[104:105], 0, v[106:107]
	v_add_co_u32_e32 v2, vcc, 0x3000, v2
	v_cvt_pk_f16_f32 v115, v110, v111
	s_nop 0
	v_addc_co_u32_e32 v3, vcc, 0, v3, vcc
	v_cvt_pk_f16_f32 v114, v112, v113
	v_cvt_pk_f16_f32 v112, v108, v109
	v_cvt_pk_f16_f32 v113, v6, v7
	s_waitcnt vmcnt(0) lgkmcnt(0)
	s_nop 0
	v_mfma_f32_16x16x32_f16 v[100:103], v[230:233], v[112:115], v[100:103]
	v_mfma_f32_16x16x32_f16 v[92:95], v[234:237], v[112:115], v[92:95]
	v_mfma_f32_16x16x32_f16 v[96:99], v[238:241], v[112:115], v[96:99]
	v_mfma_f32_16x16x32_f16 v[88:91], v[242:245], v[112:115], v[88:91]

; #define MFMA16(a, b, c) __builtin_amdgcn_mfma_f32_16x16x32_f16((a), (b), (c), 0, 0, 0)
; DI void attn_phase(const Params& p, const int layer, const int wid_s) {
;     ...
;         for (int st = 0; st < 4; ++st) {
;           if (2 * st * 256 > t0 - 16) continue;
;           const half8 pf = {(h16)s[2 * st][0], (h16)s[2 * st][1], (h16)s[2 * st][2], (h16)s[2 * st][3],
;                             (h16)s[2 * st + 1][0], (h16)s[2 * st + 1][1], (h16)s[2 * st + 1][2], (h16)s[2 * st + 1][3]};
; #pragma unroll
;           for (int dt = 0; dt < 4; ++dt) {
;             const half8 vf = *(const half8*)(vcb + ((st * 64) + dt * 16 + fr) * 32 + fq * 8);
;             o[dt] = MFMA16(vf, pf, o[dt]);
;           }
.LBB0_285:
	v_mov_b32_e32 v107, v1
	v_lshl_add_u64 v[2:3], v[104:105], 0, v[106:107]
	v_add_co_u32_e32 v2, vcc, 0x2000, v2
	v_cvt_pk_f16_f32 v126, v124, v125
	s_nop 0
	v_addc_co_u32_e32 v3, vcc, 0, v3, vcc
	v_cvt_pk_f16_f32 v125, v114, v115
	v_cvt_pk_f16_f32 v124, v116, v117
	v_cvt_pk_f16_f32 v127, v118, v119
	s_waitcnt vmcnt(0) lgkmcnt(0)
	s_nop 0
	v_mfma_f32_16x16x32_f16 v[100:103], v[214:217], v[124:127], v[100:103]
	v_mfma_f32_16x16x32_f16 v[92:95], v[218:221], v[124:127], v[92:95]
	v_mfma_f32_16x16x32_f16 v[96:99], v[222:225], v[124:127], v[96:99]
	v_mfma_f32_16x16x32_f16 v[88:91], v[226:229], v[124:127], v[88:91]
	s_and_b64 vcc, exec, s[46:47]
	s_cbranch_vccz .LBB0_271
	s_branch .LBB0_272

; #define MFMA16(a, b, c) __builtin_amdgcn_mfma_f32_16x16x32_f16((a), (b), (c), 0, 0, 0)
; DI void attn_phase(const Params& p, const int layer, const int wid_s) {
;     ...
;         for (int st = 0; st < 4; ++st) {
;           if (2 * st * 256 > t0 - 16) continue;
;           const half8 pf = {(h16)s[2 * st][0], (h16)s[2 * st][1], (h16)s[2 * st][2], (h16)s[2 * st][3],
;                             (h16)s[2 * st + 1][0], (h16)s[2 * st + 1][1], (h16)s[2 * st + 1][2], (h16)s[2 * st + 1][3]};
; #pragma unroll
;           for (int dt = 0; dt < 4; ++dt) {
;             const half8 vf = *(const half8*)(vcb + ((st * 64) + dt * 16 + fr) * 32 + fq * 8);
;             o[dt] = MFMA16(vf, pf, o[dt]);
;           }
.LBB0_328:
	v_mov_b32_e32 v107, v1
	v_lshl_add_u64 v[2:3], v[104:105], 0, v[106:107]
	v_add_co_u32_e32 v2, vcc, 0x1000, v2
	v_cvt_pk_f16_f32 v62, v60, v61
	s_nop 0
	v_addc_co_u32_e32 v3, vcc, 0, v3, vcc
	v_cvt_pk_f16_f32 v61, v54, v55
	v_cvt_pk_f16_f32 v60, v56, v57
	v_cvt_pk_f16_f32 v63, v58, v59
	s_waitcnt vmcnt(0) lgkmcnt(0)
	s_nop 0
	v_mfma_f32_16x16x32_f16 v[36:39], v[198:201], v[60:63], v[36:39]
	v_mfma_f32_16x16x32_f16 v[28:31], v[202:205], v[60:63], v[28:31]
	v_mfma_f32_16x16x32_f16 v[32:35], v[206:209], v[60:63], v[32:35]
	v_mfma_f32_16x16x32_f16 v[24:27], v[210:213], v[60:63], v[24:27]

; #define MFMA16(a, b, c) __builtin_amdgcn_mfma_f32_16x16x32_f16((a), (b), (c), 0, 0, 0)
; DI void attn_phase(const Params& p, const int layer, const int wid_s) {
;     ...
;         for (int st = 0; st < 4; ++st) {
;           if (2 * st * 256 > t0 - 16) continue;
;           const half8 pf = {(h16)s[2 * st][0], (h16)s[2 * st][1], (h16)s[2 * st][2], (h16)s[2 * st][3],
;                             (h16)s[2 * st + 1][0], (h16)s[2 * st + 1][1], (h16)s[2 * st + 1][2], (h16)s[2 * st + 1][3]};
; #pragma unroll
;           for (int dt = 0; dt < 4; ++dt) {
;             const half8 vf = *(const half8*)(vcb + ((st * 64) + dt * 16 + fr) * 32 + fq * 8);
;             o[dt] = MFMA16(vf, pf, o[dt]);
;           }
.LBB0_331:
	v_mov_b32_e32 v107, v1
	v_lshl_add_u64 v[2:3], v[104:105], 0, v[106:107]
	v_add_co_u32_e32 v2, vcc, 0x3000, v2
	v_cvt_pk_f16_f32 v47, v42, v43
	s_nop 0
	v_addc_co_u32_e32 v3, vcc, 0, v3, vcc
	v_cvt_pk_f16_f32 v46, v44, v45
	v_cvt_pk_f16_f32 v44, v40, v41
	v_cvt_pk_f16_f32 v45, v6, v7
	s_waitcnt vmcnt(0) lgkmcnt(0)
	s_nop 0
	v_mfma_f32_16x16x32_f16 v[36:39], v[230:233], v[44:47], v[36:39]
	v_mfma_f32_16x16x32_f16 v[28:31], v[234:237], v[44:47], v[28:31]
	v_mfma_f32_16x16x32_f16 v[32:35], v[238:241], v[44:47], v[32:35]
	v_mfma_f32_16x16x32_f16 v[24:27], v[242:245], v[44:47], v[24:27]

; #define MFMA16(a, b, c) __builtin_amdgcn_mfma_f32_16x16x32_f16((a), (b), (c), 0, 0, 0)
; DI void attn_phase(const Params& p, const int layer, const int wid_s) {
;     ...
;         for (int st = 0; st < 4; ++st) {
;           if (2 * st * 256 > t0 - 16) continue;
;           const half8 pf = {(h16)s[2 * st][0], (h16)s[2 * st][1], (h16)s[2 * st][2], (h16)s[2 * st][3],
;                             (h16)s[2 * st + 1][0], (h16)s[2 * st + 1][1], (h16)s[2 * st + 1][2], (h16)s[2 * st + 1][3]};
; #pragma unroll
;           for (int dt = 0; dt < 4; ++dt) {
;             const half8 vf = *(const half8*)(vcb + ((st * 64) + dt * 16 + fr) * 32 + fq * 8);
;             o[dt] = MFMA16(vf, pf, o[dt]);
;           }
.LBB0_372:
	v_mov_b32_e32 v107, v1
	v_lshl_add_u64 v[2:3], v[104:105], 0, v[106:107]
	v_add_co_u32_e32 v2, vcc, 0x2000, v2
	v_cvt_pk_f16_f32 v54, v52, v53
	s_nop 0
	v_addc_co_u32_e32 v3, vcc, 0, v3, vcc
	v_cvt_pk_f16_f32 v53, v46, v47
	v_cvt_pk_f16_f32 v52, v48, v49
	v_cvt_pk_f16_f32 v55, v50, v51
	s_waitcnt vmcnt(0) lgkmcnt(0)
	s_nop 0
	v_mfma_f32_16x16x32_f16 v[36:39], v[214:217], v[52:55], v[36:39]
	v_mfma_f32_16x16x32_f16 v[28:31], v[218:221], v[52:55], v[28:31]
	v_mfma_f32_16x16x32_f16 v[32:35], v[222:225], v[52:55], v[32:35]
	v_mfma_f32_16x16x32_f16 v[24:27], v[226:229], v[52:55], v[24:27]
	s_and_b64 vcc, exec, s[46:47]
	s_cbranch_vccz .LBB0_331
	s_branch .LBB0_332

; #define MFMA16(a, b, c) __builtin_amdgcn_mfma_f32_16x16x32_f16((a), (b), (c), 0, 0, 0)
; DI void mixers_phase(const Params& p, const int l, const int wid_s) {
;     ...
; #pragma unroll 4
;       for (int s = half * 32; s < half * 32 + 32; ++s) {
;         const int i = s >> 1, d = (s & 1) * 32 + fq * 8;
;         half8 zf = *(const half8*)(zb + (size_t)i * LDH + d);
;         const half8 pf = *(const half8*)(pe + i * 64 + d);
;         zf = zf + pf;
; #pragma unroll
;         for (int e = 0; e < 4; ++e) {
;           const half8 wf = *(const half8*)(w1t + (size_t)(e * 16 + fr) * 2048 + s * 32 + fq * 8);
;           a1[e] = MFMA16(wf, zf, a1[e]);
;         }
;       }
.LBB0_402:
	v_ashrrev_i32_e32 v14, 1, v0
	v_mad_i64_i32 v[42:43], s[0:1], v14, s3, v[30:31]
	s_mov_b32 s0, 0x3008000
	v_add_co_u32_e64 v44, s[0:1], s0, v40
	s_nop 1
	v_addc_co_u32_e64 v45, s[0:1], 0, v41, s[0:1]
	s_mov_b32 s0, 0x2f00000
	v_add_co_u32_e64 v46, s[0:1], s0, v38
	s_nop 1
	v_addc_co_u32_e64 v47, s[0:1], 0, v39, s[0:1]
	s_mov_b32 s0, 0x2f10000
	v_add_co_u32_e64 v48, s[0:1], s0, v38
	s_nop 1
	v_addc_co_u32_e64 v49, s[0:1], 0, v39, s[0:1]
	s_mov_b32 s0, 0x2f20000
	v_add_co_u32_e64 v52, s[0:1], s0, v38
	s_nop 1
	v_addc_co_u32_e64 v53, s[0:1], 0, v39, s[0:1]
	s_mov_b32 s0, 0x2f30000
	v_add_co_u32_e64 v54, s[0:1], s0, v38
	s_nop 1
	v_addc_co_u32_e64 v55, s[0:1], 0, v39, s[0:1]
	s_movk_i32 s6, 0x1400
	s_mov_b32 s7, 0
	global_load_dwordx4 v[198:201], v[42:43], off
	global_load_dwordx4 v[202:205], v[44:45], off offset:0
	global_load_dwordx4 v[206:209], v[46:47], off offset:0
	global_load_dwordx4 v[210:213], v[48:49], off offset:0
	global_load_dwordx4 v[214:217], v[52:53], off offset:0
	global_load_dwordx4 v[218:221], v[54:55], off offset:0
	global_load_dwordx4 v[222:225], v[42:43], off offset:64
	global_load_dwordx4 v[226:229], v[44:45], off offset:64
	global_load_dwordx4 v[230:233], v[46:47], off offset:64
	global_load_dwordx4 v[234:237], v[48:49], off offset:64
	global_load_dwordx4 v[238:241], v[52:53], off offset:64
	global_load_dwordx4 v[242:245], v[54:55], off offset:64
	v_lshl_add_u64 v[42:43], v[42:43], 0, s[6:7]
	global_load_dwordx4 v[120:123], v[42:43], off
	global_load_dwordx4 v[124:127], v[44:45], off offset:128
	global_load_dwordx4 v[128:131], v[46:47], off offset:128
	global_load_dwordx4 v[132:135], v[48:49], off offset:128
	global_load_dwordx4 v[178:181], v[52:53], off offset:128
	global_load_dwordx4 v[182:185], v[54:55], off offset:128
	global_load_dwordx4 v[186:189], v[42:43], off offset:64
	global_load_dwordx4 v[190:193], v[44:45], off offset:192
	global_load_dwordx4 v[194:197], v[46:47], off offset:192
	global_load_dwordx4 v[138:141], v[48:49], off offset:192
	global_load_dwordx4 v[142:145], v[52:53], off offset:192
	global_load_dwordx4 v[150:153], v[54:55], off offset:192
	s_waitcnt vmcnt(12)
	v_pk_add_f16 v198, v198, v202
	v_pk_add_f16 v199, v199, v203
	v_pk_add_f16 v200, v200, v204
	v_pk_add_f16 v201, v201, v205
	v_pk_add_f16 v222, v222, v226
	v_pk_add_f16 v223, v223, v227
	v_pk_add_f16 v224, v224, v228
	v_pk_add_f16 v225, v225, v229
	v_mfma_f32_16x16x32_f16 v[10:13], v[206:209], v[198:201], v[10:13]
	v_mfma_f32_16x16x32_f16 v[6:9], v[210:213], v[198:201], v[6:9]
	v_mfma_f32_16x16x32_f16 v[24:27], v[214:217], v[198:201], v[24:27]
	v_mfma_f32_16x16x32_f16 v[20:23], v[218:221], v[198:201], v[20:23]
	v_mfma_f32_16x16x32_f16 v[10:13], v[230:233], v[222:225], v[10:13]
	v_mfma_f32_16x16x32_f16 v[6:9], v[234:237], v[222:225], v[6:9]
	v_mfma_f32_16x16x32_f16 v[24:27], v[238:241], v[222:225], v[24:27]
	v_mfma_f32_16x16x32_f16 v[20:23], v[242:245], v[222:225], v[20:23]
	v_lshl_add_u64 v[42:43], v[42:43], 0, s[6:7]
	global_load_dwordx4 v[198:201], v[42:43], off
	global_load_dwordx4 v[202:205], v[44:45], off offset:256
	global_load_dwordx4 v[206:209], v[46:47], off offset:256
	global_load_dwordx4 v[210:213], v[48:49], off offset:256
	global_load_dwordx4 v[214:217], v[52:53], off offset:256
	global_load_dwordx4 v[218:221], v[54:55], off offset:256
	global_load_dwordx4 v[222:225], v[42:43], off offset:64
	global_load_dwordx4 v[226:229], v[44:45], off offset:320
	global_load_dwordx4 v[230:233], v[46:47], off offset:320
	global_load_dwordx4 v[234:237], v[48:49], off offset:320
	global_load_dwordx4 v[238:241], v[52:53], off offset:320
	global_load_dwordx4 v[242:245], v[54:55], off offset:320
	s_waitcnt vmcnt(12)
	v_pk_add_f16 v120, v120, v124
	v_pk_add_f16 v121, v121, v125
	v_pk_add_f16 v122, v122, v126
	v_pk_add_f16 v123, v123, v127
	v_pk_add_f16 v186, v186, v190
	v_pk_add_f16 v187, v187, v191
	v_pk_add_f16 v188, v188, v192
	v_pk_add_f16 v189, v189, v193
	v_mfma_f32_16x16x32_f16 v[10:13], v[128:131], v[120:123], v[10:13]
	v_mfma_f32_16x16x32_f16 v[6:9], v[132:135], v[120:123], v[6:9]
	v_mfma_f32_16x16x32_f16 v[24:27], v[178:181], v[120:123], v[24:27]
	v_mfma_f32_16x16x32_f16 v[20:23], v[182:185], v[120:123], v[20:23]
	v_mfma_f32_16x16x32_f16 v[10:13], v[194:197], v[186:189], v[10:13]
	v_mfma_f32_16x16x32_f16 v[6:9], v[138:141], v[186:189], v[6:9]
	v_mfma_f32_16x16x32_f16 v[24:27], v[142:145], v[186:189], v[24:27]
	v_mfma_f32_16x16x32_f16 v[20:23], v[150:153], v[186:189], v[20:23]
	v_lshl_add_u64 v[42:43], v[42:43], 0, s[6:7]
	global_load_dwordx4 v[120:123], v[42:43], off
	global_load_dwordx4 v[124:127], v[44:45], off offset:384
	global_load_dwordx4 v[128:131], v[46:47], off offset:384
	global_load_dwordx4 v[132:135], v[48:49], off offset:384
	global_load_dwordx4 v[178:181], v[52:53], off offset:384
	global_load_dwordx4 v[182:185], v[54:55], off offset:384
	global_load_dwordx4 v[186:189], v[42:43], off offset:64
	global_load_dwordx4 v[190:193], v[44:45], off offset:448
	global_load_dwordx4 v[194:197], v[46:47], off offset:448
	global_load_dwordx4 v[138:141], v[48:49], off offset:448
	global_load_dwordx4 v[142:145], v[52:53], off offset:448
	global_load_dwordx4 v[150:153], v[54:55], off offset:448
	s_waitcnt vmcnt(12)
; #define MFMA16(a, b, c) __builtin_amdgcn_mfma_f32_16x16x32_f16((a), (b), (c), 0, 0, 0)
; DI void mixers_phase(const Params& p, const int l, const int wid_s) {
;     ...
; #pragma unroll 4
;       for (int s = half * 32; s < half * 32 + 32; ++s) {
;         const int i = s >> 1, d = (s & 1) * 32 + fq * 8;
;         half8 zf = *(const half8*)(zb + (size_t)i * LDH + d);
;         const half8 pf = *(const half8*)(pe + i * 64 + d);
;         zf = zf + pf;
; #pragma unroll
;         for (int e = 0; e < 4; ++e) {
;           const half8 wf = *(const half8*)(w1t + (size_t)(e * 16 + fr) * 2048 + s * 32 + fq * 8);
;           a1[e] = MFMA16(wf, zf, a1[e]);
;         }
;       }
	v_pk_add_f16 v198, v198, v202
	v_pk_add_f16 v199, v199, v203
	v_pk_add_f16 v200, v200, v204
	v_pk_add_f16 v201, v201, v205
	v_pk_add_f16 v222, v222, v226
	v_pk_add_f16 v223, v223, v227
	v_pk_add_f16 v224, v224, v228
	v_pk_add_f16 v225, v225, v229
	v_mfma_f32_16x16x32_f16 v[10:13], v[206:209], v[198:201], v[10:13]
	v_mfma_f32_16x16x32_f16 v[6:9], v[210:213], v[198:201], v[6:9]
	v_mfma_f32_16x16x32_f16 v[24:27], v[214:217], v[198:201], v[24:27]
	v_mfma_f32_16x16x32_f16 v[20:23], v[218:221], v[198:201], v[20:23]
	v_mfma_f32_16x16x32_f16 v[10:13], v[230:233], v[222:225], v[10:13]
	v_mfma_f32_16x16x32_f16 v[6:9], v[234:237], v[222:225], v[6:9]
	v_mfma_f32_16x16x32_f16 v[24:27], v[238:241], v[222:225], v[24:27]
	v_mfma_f32_16x16x32_f16 v[20:23], v[242:245], v[222:225], v[20:23]
	v_lshl_add_u64 v[42:43], v[42:43], 0, s[6:7]
	global_load_dwordx4 v[198:201], v[42:43], off
	global_load_dwordx4 v[202:205], v[44:45], off offset:512
	global_load_dwordx4 v[206:209], v[46:47], off offset:512
	global_load_dwordx4 v[210:213], v[48:49], off offset:512
	global_load_dwordx4 v[214:217], v[52:53], off offset:512
	global_load_dwordx4 v[218:221], v[54:55], off offset:512
	global_load_dwordx4 v[222:225], v[42:43], off offset:64
	global_load_dwordx4 v[226:229], v[44:45], off offset:576
	global_load_dwordx4 v[230:233], v[46:47], off offset:576
	global_load_dwordx4 v[234:237], v[48:49], off offset:576
	global_load_dwordx4 v[238:241], v[52:53], off offset:576
	global_load_dwordx4 v[242:245], v[54:55], off offset:576
	s_waitcnt vmcnt(12)
	v_pk_add_f16 v120, v120, v124
	v_pk_add_f16 v121, v121, v125
	v_pk_add_f16 v122, v122, v126
	v_pk_add_f16 v123, v123, v127
	v_pk_add_f16 v186, v186, v190
	v_pk_add_f16 v187, v187, v191
	v_pk_add_f16 v188, v188, v192
	v_pk_add_f16 v189, v189, v193
	v_mfma_f32_16x16x32_f16 v[10:13], v[128:131], v[120:123], v[10:13]
	v_mfma_f32_16x16x32_f16 v[6:9], v[132:135], v[120:123], v[6:9]
	v_mfma_f32_16x16x32_f16 v[24:27], v[178:181], v[120:123], v[24:27]
	v_mfma_f32_16x16x32_f16 v[20:23], v[182:185], v[120:123], v[20:23]
	v_mfma_f32_16x16x32_f16 v[10:13], v[194:197], v[186:189], v[10:13]
	v_mfma_f32_16x16x32_f16 v[6:9], v[138:141], v[186:189], v[6:9]
	v_mfma_f32_16x16x32_f16 v[24:27], v[142:145], v[186:189], v[24:27]
	v_mfma_f32_16x16x32_f16 v[20:23], v[150:153], v[186:189], v[20:23]
	v_lshl_add_u64 v[42:43], v[42:43], 0, s[6:7]
	global_load_dwordx4 v[120:123], v[42:43], off
	global_load_dwordx4 v[124:127], v[44:45], off offset:640
	global_load_dwordx4 v[128:131], v[46:47], off offset:640
	global_load_dwordx4 v[132:135], v[48:49], off offset:640
	global_load_dwordx4 v[178:181], v[52:53], off offset:640
	global_load_dwordx4 v[182:185], v[54:55], off offset:640
	global_load_dwordx4 v[186:189], v[42:43], off offset:64
	global_load_dwordx4 v[190:193], v[44:45], off offset:704
	global_load_dwordx4 v[194:197], v[46:47], off offset:704
	global_load_dwordx4 v[138:141], v[48:49], off offset:704
	global_load_dwordx4 v[142:145], v[52:53], off offset:704
	global_load_dwordx4 v[150:153], v[54:55], off offset:704
	s_waitcnt vmcnt(12)
	v_pk_add_f16 v198, v198, v202
	v_pk_add_f16 v199, v199, v203
	v_pk_add_f16 v200, v200, v204
	v_pk_add_f16 v201, v201, v205
	v_pk_add_f16 v222, v222, v226
	v_pk_add_f16 v223, v223, v227
	v_pk_add_f16 v224, v224, v228
	v_pk_add_f16 v225, v225, v229
	v_mfma_f32_16x16x32_f16 v[10:13], v[206:209], v[198:201], v[10:13]
	v_mfma_f32_16x16x32_f16 v[6:9], v[210:213], v[198:201], v[6:9]
	v_mfma_f32_16x16x32_f16 v[24:27], v[214:217], v[198:201], v[24:27]
	v_mfma_f32_16x16x32_f16 v[20:23], v[218:221], v[198:201], v[20:23]
	v_mfma_f32_16x16x32_f16 v[10:13], v[230:233], v[222:225], v[10:13]
	v_mfma_f32_16x16x32_f16 v[6:9], v[234:237], v[222:225], v[6:9]
	v_mfma_f32_16x16x32_f16 v[24:27], v[238:241], v[222:225], v[24:27]
	v_mfma_f32_16x16x32_f16 v[20:23], v[242:245], v[222:225], v[20:23]
	v_lshl_add_u64 v[42:43], v[42:43], 0, s[6:7]
	global_load_dwordx4 v[198:201], v[42:43], off
	global_load_dwordx4 v[202:205], v[44:45], off offset:768
	global_load_dwordx4 v[206:209], v[46:47], off offset:768
	global_load_dwordx4 v[210:213], v[48:49], off offset:768
	global_load_dwordx4 v[214:217], v[52:53], off offset:768
	global_load_dwordx4 v[218:221], v[54:55], off offset:768
	global_load_dwordx4 v[222:225], v[42:43], off offset:64
	global_load_dwordx4 v[226:229], v[44:45], off offset:832
	global_load_dwordx4 v[230:233], v[46:47], off offset:832
	global_load_dwordx4 v[234:237], v[48:49], off offset:832
	global_load_dwordx4 v[238:241], v[52:53], off offset:832
	global_load_dwordx4 v[242:245], v[54:55], off offset:832
	s_waitcnt vmcnt(12)
	v_pk_add_f16 v120, v120, v124
	v_pk_add_f16 v121, v121, v125
	v_pk_add_f16 v122, v122, v126
	v_pk_add_f16 v123, v123, v127
	v_pk_add_f16 v186, v186, v190
	v_pk_add_f16 v187, v187, v191
	v_pk_add_f16 v188, v188, v192
	v_pk_add_f16 v189, v189, v193
	v_mfma_f32_16x16x32_f16 v[10:13], v[128:131], v[120:123], v[10:13]
	v_mfma_f32_16x16x32_f16 v[6:9], v[132:135], v[120:123], v[6:9]
	v_mfma_f32_16x16x32_f16 v[24:27], v[178:181], v[120:123], v[24:27]
	v_mfma_f32_16x16x32_f16 v[20:23], v[182:185], v[120:123], v[20:23]
	v_mfma_f32_16x16x32_f16 v[10:13], v[194:197], v[186:189], v[10:13]
	v_mfma_f32_16x16x32_f16 v[6:9], v[138:141], v[186:189], v[6:9]
	v_mfma_f32_16x16x32_f16 v[24:27], v[142:145], v[186:189], v[24:27]
	v_mfma_f32_16x16x32_f16 v[20:23], v[150:153], v[186:189], v[20:23]
	v_lshl_add_u64 v[42:43], v[42:43], 0, s[6:7]
	global_load_dwordx4 v[120:123], v[42:43], off
	global_load_dwordx4 v[124:127], v[44:45], off offset:896
	global_load_dwordx4 v[128:131], v[46:47], off offset:896
	global_load_dwordx4 v[132:135], v[48:49], off offset:896
	global_load_dwordx4 v[178:181], v[52:53], off offset:896
	global_load_dwordx4 v[182:185], v[54:55], off offset:896
	global_load_dwordx4 v[186:189], v[42:43], off offset:64
	global_load_dwordx4 v[190:193], v[44:45], off offset:960
	global_load_dwordx4 v[194:197], v[46:47], off offset:960
	global_load_dwordx4 v[138:141], v[48:49], off offset:960
	global_load_dwordx4 v[142:145], v[52:53], off offset:960
	global_load_dwordx4 v[150:153], v[54:55], off offset:960
	s_waitcnt vmcnt(12)
; #define MFMA16(a, b, c) __builtin_amdgcn_mfma_f32_16x16x32_f16((a), (b), (c), 0, 0, 0)
; DI void mixers_phase(const Params& p, const int l, const int wid_s) {
;     ...
; #pragma unroll 4
;       for (int s = half * 32; s < half * 32 + 32; ++s) {
;         const int i = s >> 1, d = (s & 1) * 32 + fq * 8;
;         half8 zf = *(const half8*)(zb + (size_t)i * LDH + d);
;         const half8 pf = *(const half8*)(pe + i * 64 + d);
;         zf = zf + pf;
; #pragma unroll
;         for (int e = 0; e < 4; ++e) {
;           const half8 wf = *(const half8*)(w1t + (size_t)(e * 16 + fr) * 2048 + s * 32 + fq * 8);
;           a1[e] = MFMA16(wf, zf, a1[e]);
;         }
;       }
	v_pk_add_f16 v198, v198, v202
	v_pk_add_f16 v199, v199, v203
	v_pk_add_f16 v200, v200, v204
	v_pk_add_f16 v201, v201, v205
	v_pk_add_f16 v222, v222, v226
	v_pk_add_f16 v223, v223, v227
	v_pk_add_f16 v224, v224, v228
	v_pk_add_f16 v225, v225, v229
	v_mfma_f32_16x16x32_f16 v[10:13], v[206:209], v[198:201], v[10:13]
	v_mfma_f32_16x16x32_f16 v[6:9], v[210:213], v[198:201], v[6:9]
	v_mfma_f32_16x16x32_f16 v[24:27], v[214:217], v[198:201], v[24:27]
	v_mfma_f32_16x16x32_f16 v[20:23], v[218:221], v[198:201], v[20:23]
	v_mfma_f32_16x16x32_f16 v[10:13], v[230:233], v[222:225], v[10:13]
	v_mfma_f32_16x16x32_f16 v[6:9], v[234:237], v[222:225], v[6:9]
	v_mfma_f32_16x16x32_f16 v[24:27], v[238:241], v[222:225], v[24:27]
	v_mfma_f32_16x16x32_f16 v[20:23], v[242:245], v[222:225], v[20:23]
	v_lshl_add_u64 v[42:43], v[42:43], 0, s[6:7]
	global_load_dwordx4 v[198:201], v[42:43], off
	global_load_dwordx4 v[202:205], v[44:45], off offset:1024
	global_load_dwordx4 v[206:209], v[46:47], off offset:1024
	global_load_dwordx4 v[210:213], v[48:49], off offset:1024
	global_load_dwordx4 v[214:217], v[52:53], off offset:1024
	global_load_dwordx4 v[218:221], v[54:55], off offset:1024
	global_load_dwordx4 v[222:225], v[42:43], off offset:64
	global_load_dwordx4 v[226:229], v[44:45], off offset:1088
	global_load_dwordx4 v[230:233], v[46:47], off offset:1088
	global_load_dwordx4 v[234:237], v[48:49], off offset:1088
	global_load_dwordx4 v[238:241], v[52:53], off offset:1088
	global_load_dwordx4 v[242:245], v[54:55], off offset:1088
	s_waitcnt vmcnt(12)
	v_pk_add_f16 v120, v120, v124
	v_pk_add_f16 v121, v121, v125
	v_pk_add_f16 v122, v122, v126
	v_pk_add_f16 v123, v123, v127
	v_pk_add_f16 v186, v186, v190
	v_pk_add_f16 v187, v187, v191
	v_pk_add_f16 v188, v188, v192
	v_pk_add_f16 v189, v189, v193
	v_mfma_f32_16x16x32_f16 v[10:13], v[128:131], v[120:123], v[10:13]
	v_mfma_f32_16x16x32_f16 v[6:9], v[132:135], v[120:123], v[6:9]
	v_mfma_f32_16x16x32_f16 v[24:27], v[178:181], v[120:123], v[24:27]
	v_mfma_f32_16x16x32_f16 v[20:23], v[182:185], v[120:123], v[20:23]
	v_mfma_f32_16x16x32_f16 v[10:13], v[194:197], v[186:189], v[10:13]
	v_mfma_f32_16x16x32_f16 v[6:9], v[138:141], v[186:189], v[6:9]
	v_mfma_f32_16x16x32_f16 v[24:27], v[142:145], v[186:189], v[24:27]
	v_mfma_f32_16x16x32_f16 v[20:23], v[150:153], v[186:189], v[20:23]
	v_lshl_add_u64 v[42:43], v[42:43], 0, s[6:7]
	global_load_dwordx4 v[120:123], v[42:43], off
	global_load_dwordx4 v[124:127], v[44:45], off offset:1152
	global_load_dwordx4 v[128:131], v[46:47], off offset:1152
	global_load_dwordx4 v[132:135], v[48:49], off offset:1152
	global_load_dwordx4 v[178:181], v[52:53], off offset:1152
	global_load_dwordx4 v[182:185], v[54:55], off offset:1152
	global_load_dwordx4 v[186:189], v[42:43], off offset:64
	global_load_dwordx4 v[190:193], v[44:45], off offset:1216
	global_load_dwordx4 v[194:197], v[46:47], off offset:1216
	global_load_dwordx4 v[138:141], v[48:49], off offset:1216
	global_load_dwordx4 v[142:145], v[52:53], off offset:1216
	global_load_dwordx4 v[150:153], v[54:55], off offset:1216
	s_waitcnt vmcnt(12)
	v_pk_add_f16 v198, v198, v202
	v_pk_add_f16 v199, v199, v203
	v_pk_add_f16 v200, v200, v204
	v_pk_add_f16 v201, v201, v205
	v_pk_add_f16 v222, v222, v226
	v_pk_add_f16 v223, v223, v227
	v_pk_add_f16 v224, v224, v228
	v_pk_add_f16 v225, v225, v229
	v_mfma_f32_16x16x32_f16 v[10:13], v[206:209], v[198:201], v[10:13]
	v_mfma_f32_16x16x32_f16 v[6:9], v[210:213], v[198:201], v[6:9]
	v_mfma_f32_16x16x32_f16 v[24:27], v[214:217], v[198:201], v[24:27]
	v_mfma_f32_16x16x32_f16 v[20:23], v[218:221], v[198:201], v[20:23]
	v_mfma_f32_16x16x32_f16 v[10:13], v[230:233], v[222:225], v[10:13]
	v_mfma_f32_16x16x32_f16 v[6:9], v[234:237], v[222:225], v[6:9]
	v_mfma_f32_16x16x32_f16 v[24:27], v[238:241], v[222:225], v[24:27]
	v_mfma_f32_16x16x32_f16 v[20:23], v[242:245], v[222:225], v[20:23]
	v_lshl_add_u64 v[42:43], v[42:43], 0, s[6:7]
	global_load_dwordx4 v[198:201], v[42:43], off
	global_load_dwordx4 v[202:205], v[44:45], off offset:1280
	global_load_dwordx4 v[206:209], v[46:47], off offset:1280
	global_load_dwordx4 v[210:213], v[48:49], off offset:1280
	global_load_dwordx4 v[214:217], v[52:53], off offset:1280
	global_load_dwordx4 v[218:221], v[54:55], off offset:1280
	global_load_dwordx4 v[222:225], v[42:43], off offset:64
	global_load_dwordx4 v[226:229], v[44:45], off offset:1344
	global_load_dwordx4 v[230:233], v[46:47], off offset:1344
	global_load_dwordx4 v[234:237], v[48:49], off offset:1344
	global_load_dwordx4 v[238:241], v[52:53], off offset:1344
	global_load_dwordx4 v[242:245], v[54:55], off offset:1344
	s_waitcnt vmcnt(12)
	v_pk_add_f16 v120, v120, v124
	v_pk_add_f16 v121, v121, v125
	v_pk_add_f16 v122, v122, v126
	v_pk_add_f16 v123, v123, v127
	v_pk_add_f16 v186, v186, v190
	v_pk_add_f16 v187, v187, v191
	v_pk_add_f16 v188, v188, v192
	v_pk_add_f16 v189, v189, v193
	v_mfma_f32_16x16x32_f16 v[10:13], v[128:131], v[120:123], v[10:13]
	v_mfma_f32_16x16x32_f16 v[6:9], v[132:135], v[120:123], v[6:9]
	v_mfma_f32_16x16x32_f16 v[24:27], v[178:181], v[120:123], v[24:27]
	v_mfma_f32_16x16x32_f16 v[20:23], v[182:185], v[120:123], v[20:23]
	v_mfma_f32_16x16x32_f16 v[10:13], v[194:197], v[186:189], v[10:13]
	v_mfma_f32_16x16x32_f16 v[6:9], v[138:141], v[186:189], v[6:9]
	v_mfma_f32_16x16x32_f16 v[24:27], v[142:145], v[186:189], v[24:27]
	v_mfma_f32_16x16x32_f16 v[20:23], v[150:153], v[186:189], v[20:23]
	v_lshl_add_u64 v[42:43], v[42:43], 0, s[6:7]
	global_load_dwordx4 v[120:123], v[42:43], off
	global_load_dwordx4 v[124:127], v[44:45], off offset:1408
	global_load_dwordx4 v[128:131], v[46:47], off offset:1408
	global_load_dwordx4 v[132:135], v[48:49], off offset:1408
	global_load_dwordx4 v[178:181], v[52:53], off offset:1408
	global_load_dwordx4 v[182:185], v[54:55], off offset:1408
	global_load_dwordx4 v[186:189], v[42:43], off offset:64
	global_load_dwordx4 v[190:193], v[44:45], off offset:1472
	global_load_dwordx4 v[194:197], v[46:47], off offset:1472
	global_load_dwordx4 v[138:141], v[48:49], off offset:1472
	global_load_dwordx4 v[142:145], v[52:53], off offset:1472
	global_load_dwordx4 v[150:153], v[54:55], off offset:1472
	s_waitcnt vmcnt(12)
; #define MFMA16(a, b, c) __builtin_amdgcn_mfma_f32_16x16x32_f16((a), (b), (c), 0, 0, 0)
; DI void mixers_phase(const Params& p, const int l, const int wid_s) {
;     ...
; #pragma unroll 4
;       for (int s = half * 32; s < half * 32 + 32; ++s) {
;         const int i = s >> 1, d = (s & 1) * 32 + fq * 8;
;         half8 zf = *(const half8*)(zb + (size_t)i * LDH + d);
;         const half8 pf = *(const half8*)(pe + i * 64 + d);
;         zf = zf + pf;
; #pragma unroll
;         for (int e = 0; e < 4; ++e) {
;           const half8 wf = *(const half8*)(w1t + (size_t)(e * 16 + fr) * 2048 + s * 32 + fq * 8);
;           a1[e] = MFMA16(wf, zf, a1[e]);
;         }
;       }
	v_pk_add_f16 v198, v198, v202
	v_pk_add_f16 v199, v199, v203
	v_pk_add_f16 v200, v200, v204
	v_pk_add_f16 v201, v201, v205
	v_pk_add_f16 v222, v222, v226
	v_pk_add_f16 v223, v223, v227
	v_pk_add_f16 v224, v224, v228
	v_pk_add_f16 v225, v225, v229
	v_mfma_f32_16x16x32_f16 v[10:13], v[206:209], v[198:201], v[10:13]
	v_mfma_f32_16x16x32_f16 v[6:9], v[210:213], v[198:201], v[6:9]
	v_mfma_f32_16x16x32_f16 v[24:27], v[214:217], v[198:201], v[24:27]
	v_mfma_f32_16x16x32_f16 v[20:23], v[218:221], v[198:201], v[20:23]
	v_mfma_f32_16x16x32_f16 v[10:13], v[230:233], v[222:225], v[10:13]
	v_mfma_f32_16x16x32_f16 v[6:9], v[234:237], v[222:225], v[6:9]
	v_mfma_f32_16x16x32_f16 v[24:27], v[238:241], v[222:225], v[24:27]
	v_mfma_f32_16x16x32_f16 v[20:23], v[242:245], v[222:225], v[20:23]
	v_lshl_add_u64 v[42:43], v[42:43], 0, s[6:7]
	global_load_dwordx4 v[198:201], v[42:43], off
	global_load_dwordx4 v[202:205], v[44:45], off offset:1536
	global_load_dwordx4 v[206:209], v[46:47], off offset:1536
	global_load_dwordx4 v[210:213], v[48:49], off offset:1536
	global_load_dwordx4 v[214:217], v[52:53], off offset:1536
	global_load_dwordx4 v[218:221], v[54:55], off offset:1536
	global_load_dwordx4 v[222:225], v[42:43], off offset:64
	global_load_dwordx4 v[226:229], v[44:45], off offset:1600
	global_load_dwordx4 v[230:233], v[46:47], off offset:1600
	global_load_dwordx4 v[234:237], v[48:49], off offset:1600
	global_load_dwordx4 v[238:241], v[52:53], off offset:1600
	global_load_dwordx4 v[242:245], v[54:55], off offset:1600
	s_waitcnt vmcnt(12)
	v_pk_add_f16 v120, v120, v124
	v_pk_add_f16 v121, v121, v125
	v_pk_add_f16 v122, v122, v126
	v_pk_add_f16 v123, v123, v127
	v_pk_add_f16 v186, v186, v190
	v_pk_add_f16 v187, v187, v191
	v_pk_add_f16 v188, v188, v192
	v_pk_add_f16 v189, v189, v193
	v_mfma_f32_16x16x32_f16 v[10:13], v[128:131], v[120:123], v[10:13]
	v_mfma_f32_16x16x32_f16 v[6:9], v[132:135], v[120:123], v[6:9]
	v_mfma_f32_16x16x32_f16 v[24:27], v[178:181], v[120:123], v[24:27]
	v_mfma_f32_16x16x32_f16 v[20:23], v[182:185], v[120:123], v[20:23]
	v_mfma_f32_16x16x32_f16 v[10:13], v[194:197], v[186:189], v[10:13]
	v_mfma_f32_16x16x32_f16 v[6:9], v[138:141], v[186:189], v[6:9]
	v_mfma_f32_16x16x32_f16 v[24:27], v[142:145], v[186:189], v[24:27]
	v_mfma_f32_16x16x32_f16 v[20:23], v[150:153], v[186:189], v[20:23]
	v_lshl_add_u64 v[42:43], v[42:43], 0, s[6:7]
	global_load_dwordx4 v[120:123], v[42:43], off
	global_load_dwordx4 v[124:127], v[44:45], off offset:1664
	global_load_dwordx4 v[128:131], v[46:47], off offset:1664
	global_load_dwordx4 v[132:135], v[48:49], off offset:1664
	global_load_dwordx4 v[178:181], v[52:53], off offset:1664
	global_load_dwordx4 v[182:185], v[54:55], off offset:1664
	global_load_dwordx4 v[186:189], v[42:43], off offset:64
	global_load_dwordx4 v[190:193], v[44:45], off offset:1728
	global_load_dwordx4 v[194:197], v[46:47], off offset:1728
	global_load_dwordx4 v[138:141], v[48:49], off offset:1728
	global_load_dwordx4 v[142:145], v[52:53], off offset:1728
	global_load_dwordx4 v[150:153], v[54:55], off offset:1728
	s_waitcnt vmcnt(12)
	v_pk_add_f16 v198, v198, v202
	v_pk_add_f16 v199, v199, v203
	v_pk_add_f16 v200, v200, v204
	v_pk_add_f16 v201, v201, v205
	v_pk_add_f16 v222, v222, v226
	v_pk_add_f16 v223, v223, v227
	v_pk_add_f16 v224, v224, v228
	v_pk_add_f16 v225, v225, v229
	v_mfma_f32_16x16x32_f16 v[10:13], v[206:209], v[198:201], v[10:13]
	v_mfma_f32_16x16x32_f16 v[6:9], v[210:213], v[198:201], v[6:9]
	v_mfma_f32_16x16x32_f16 v[24:27], v[214:217], v[198:201], v[24:27]
	v_mfma_f32_16x16x32_f16 v[20:23], v[218:221], v[198:201], v[20:23]
	v_mfma_f32_16x16x32_f16 v[10:13], v[230:233], v[222:225], v[10:13]
	v_mfma_f32_16x16x32_f16 v[6:9], v[234:237], v[222:225], v[6:9]
	v_mfma_f32_16x16x32_f16 v[24:27], v[238:241], v[222:225], v[24:27]
	v_mfma_f32_16x16x32_f16 v[20:23], v[242:245], v[222:225], v[20:23]
	v_lshl_add_u64 v[42:43], v[42:43], 0, s[6:7]
	global_load_dwordx4 v[198:201], v[42:43], off
	global_load_dwordx4 v[202:205], v[44:45], off offset:1792
	global_load_dwordx4 v[206:209], v[46:47], off offset:1792
	global_load_dwordx4 v[210:213], v[48:49], off offset:1792
	global_load_dwordx4 v[214:217], v[52:53], off offset:1792
	global_load_dwordx4 v[218:221], v[54:55], off offset:1792
	global_load_dwordx4 v[222:225], v[42:43], off offset:64
	global_load_dwordx4 v[226:229], v[44:45], off offset:1856
	global_load_dwordx4 v[230:233], v[46:47], off offset:1856
	global_load_dwordx4 v[234:237], v[48:49], off offset:1856
	global_load_dwordx4 v[238:241], v[52:53], off offset:1856
	global_load_dwordx4 v[242:245], v[54:55], off offset:1856
	s_waitcnt vmcnt(12)
; #define MFMA16(a, b, c) __builtin_amdgcn_mfma_f32_16x16x32_f16((a), (b), (c), 0, 0, 0)
; DI void mixers_phase(const Params& p, const int l, const int wid_s) {
;     ...
; #pragma unroll 4
;       for (int s = half * 32; s < half * 32 + 32; ++s) {
;         const int i = s >> 1, d = (s & 1) * 32 + fq * 8;
;         half8 zf = *(const half8*)(zb + (size_t)i * LDH + d);
;         const half8 pf = *(const half8*)(pe + i * 64 + d);
;         zf = zf + pf;
; #pragma unroll
;         for (int e = 0; e < 4; ++e) {
;           const half8 wf = *(const half8*)(w1t + (size_t)(e * 16 + fr) * 2048 + s * 32 + fq * 8);
;           a1[e] = MFMA16(wf, zf, a1[e]);
;         }
;       }
	v_pk_add_f16 v120, v120, v124
	v_pk_add_f16 v121, v121, v125
	v_pk_add_f16 v122, v122, v126
	v_pk_add_f16 v123, v123, v127
	v_pk_add_f16 v186, v186, v190
	v_pk_add_f16 v187, v187, v191
	v_pk_add_f16 v188, v188, v192
	v_pk_add_f16 v189, v189, v193
	v_mfma_f32_16x16x32_f16 v[10:13], v[128:131], v[120:123], v[10:13]
	v_mfma_f32_16x16x32_f16 v[6:9], v[132:135], v[120:123], v[6:9]
	v_mfma_f32_16x16x32_f16 v[24:27], v[178:181], v[120:123], v[24:27]
	v_mfma_f32_16x16x32_f16 v[20:23], v[182:185], v[120:123], v[20:23]
	v_mfma_f32_16x16x32_f16 v[10:13], v[194:197], v[186:189], v[10:13]
	v_mfma_f32_16x16x32_f16 v[6:9], v[138:141], v[186:189], v[6:9]
	v_mfma_f32_16x16x32_f16 v[24:27], v[142:145], v[186:189], v[24:27]
	v_mfma_f32_16x16x32_f16 v[20:23], v[150:153], v[186:189], v[20:23]
	v_lshl_add_u64 v[42:43], v[42:43], 0, s[6:7]
	global_load_dwordx4 v[120:123], v[42:43], off
	global_load_dwordx4 v[124:127], v[44:45], off offset:1920
	global_load_dwordx4 v[128:131], v[46:47], off offset:1920
	global_load_dwordx4 v[132:135], v[48:49], off offset:1920
	global_load_dwordx4 v[178:181], v[52:53], off offset:1920
	global_load_dwordx4 v[182:185], v[54:55], off offset:1920
	global_load_dwordx4 v[186:189], v[42:43], off offset:64
	global_load_dwordx4 v[190:193], v[44:45], off offset:1984
	global_load_dwordx4 v[194:197], v[46:47], off offset:1984
	global_load_dwordx4 v[138:141], v[48:49], off offset:1984
	global_load_dwordx4 v[142:145], v[52:53], off offset:1984
	global_load_dwordx4 v[150:153], v[54:55], off offset:1984
	s_waitcnt vmcnt(12)
	v_pk_add_f16 v198, v198, v202
	v_pk_add_f16 v199, v199, v203
	v_pk_add_f16 v200, v200, v204
	v_pk_add_f16 v201, v201, v205
	v_pk_add_f16 v222, v222, v226
	v_pk_add_f16 v223, v223, v227
	v_pk_add_f16 v224, v224, v228
	v_pk_add_f16 v225, v225, v229
	v_mfma_f32_16x16x32_f16 v[10:13], v[206:209], v[198:201], v[10:13]
	v_mfma_f32_16x16x32_f16 v[6:9], v[210:213], v[198:201], v[6:9]
	v_mfma_f32_16x16x32_f16 v[24:27], v[214:217], v[198:201], v[24:27]
	v_mfma_f32_16x16x32_f16 v[20:23], v[218:221], v[198:201], v[20:23]
	v_mfma_f32_16x16x32_f16 v[10:13], v[230:233], v[222:225], v[10:13]
	v_mfma_f32_16x16x32_f16 v[6:9], v[234:237], v[222:225], v[6:9]
	v_mfma_f32_16x16x32_f16 v[24:27], v[238:241], v[222:225], v[24:27]
	v_mfma_f32_16x16x32_f16 v[20:23], v[242:245], v[222:225], v[20:23]
	s_waitcnt vmcnt(0)
	v_pk_add_f16 v120, v120, v124
	v_pk_add_f16 v121, v121, v125
	v_pk_add_f16 v122, v122, v126
	v_pk_add_f16 v123, v123, v127
	v_pk_add_f16 v186, v186, v190
	v_pk_add_f16 v187, v187, v191
	v_pk_add_f16 v188, v188, v192
	v_pk_add_f16 v189, v189, v193
	v_mfma_f32_16x16x32_f16 v[10:13], v[128:131], v[120:123], v[10:13]
	v_mfma_f32_16x16x32_f16 v[6:9], v[132:135], v[120:123], v[6:9]
	v_mfma_f32_16x16x32_f16 v[24:27], v[178:181], v[120:123], v[24:27]
	v_mfma_f32_16x16x32_f16 v[20:23], v[182:185], v[120:123], v[20:23]
	v_mfma_f32_16x16x32_f16 v[10:13], v[194:197], v[186:189], v[10:13]
	v_mfma_f32_16x16x32_f16 v[6:9], v[138:141], v[186:189], v[6:9]
	v_mfma_f32_16x16x32_f16 v[24:27], v[142:145], v[186:189], v[24:27]
	v_mfma_f32_16x16x32_f16 v[20:23], v[150:153], v[186:189], v[20:23]
	s_movk_i32 s6, 0x800
	s_mov_b32 s7, 0
	s_nop 7

; #define MFMA16(a, b, c) __builtin_amdgcn_mfma_f32_16x16x32_f16((a), (b), (c), 0, 0, 0)
; DI void attn_phase(const Params& p, const int layer, const int wid_s) {
;     ...
;           const half8 pf = {(h16)s[2 * st][0], (h16)s[2 * st][1], (h16)s[2 * st][2], (h16)s[2 * st][3],
;                             (h16)s[2 * st + 1][0], (h16)s[2 * st + 1][1], (h16)s[2 * st + 1][2], (h16)s[2 * st + 1][3]};
; #pragma unroll
;           for (int dt = 0; dt < 4; ++dt) {
;             const half8 vf = *(const half8*)(vcb + ((st * 64) + dt * 16 + fr) * 32 + fq * 8);
;             o[dt] = MFMA16(vf, pf, o[dt]);
;           }
	.amdhsa_kernel _Z9hymba_fwd6Params
		.amdhsa_group_segment_fixed_size 24832
		.amdhsa_private_segment_fixed_size 0
		.amdhsa_kernarg_size 424
		.amdhsa_user_sgpr_count 2
		.amdhsa_user_sgpr_dispatch_ptr 0
		.amdhsa_user_sgpr_queue_ptr 0
		.amdhsa_user_sgpr_kernarg_segment_ptr 1
		.amdhsa_user_sgpr_dispatch_id 0
		.amdhsa_user_sgpr_kernarg_preload_length 0
		.amdhsa_user_sgpr_kernarg_preload_offset 0
		.amdhsa_user_sgpr_private_segment_size 0
		.amdhsa_uses_dynamic_stack 0
		.amdhsa_enable_private_segment 0
		.amdhsa_system_sgpr_workgroup_id_x 1
		.amdhsa_system_sgpr_workgroup_id_y 0
		.amdhsa_system_sgpr_workgroup_id_z 0
		.amdhsa_system_sgpr_workgroup_info 0
		.amdhsa_system_vgpr_workitem_id 2
		.amdhsa_next_free_vgpr 256
		.amdhsa_next_free_sgpr 100
		.amdhsa_accum_offset 256
		.amdhsa_reserve_vcc 1
		.amdhsa_float_round_mode_32 0
		.amdhsa_float_round_mode_16_64 0
		.amdhsa_float_denorm_mode_32 3
		.amdhsa_float_denorm_mode_16_64 3
		.amdhsa_dx10_clamp 1
		.amdhsa_ieee_mode 1
		.amdhsa_fp16_overflow 0
		.amdhsa_tg_split 0
		.amdhsa_exception_fp_ieee_invalid_op 0
		.amdhsa_exception_fp_denorm_src 0
		.amdhsa_exception_fp_ieee_div_zero 0
		.amdhsa_exception_fp_ieee_overflow 0
		.amdhsa_exception_fp_ieee_underflow 0
		.amdhsa_exception_fp_ieee_inexact 0
		.amdhsa_exception_int_div_zero 0
	.end_amdhsa_kernel

; #define MFMA16(a, b, c) __builtin_amdgcn_mfma_f32_16x16x32_f16((a), (b), (c), 0, 0, 0)
; DI void attn_phase(const Params& p, const int layer, const int wid_s) {
;     ...
;           const half8 pf = {(h16)s[2 * st][0], (h16)s[2 * st][1], (h16)s[2 * st][2], (h16)s[2 * st][3],
;                             (h16)s[2 * st + 1][0], (h16)s[2 * st + 1][1], (h16)s[2 * st + 1][2], (h16)s[2 * st + 1][3]};
; #pragma unroll
;           for (int dt = 0; dt < 4; ++dt) {
;             const half8 vf = *(const half8*)(vcb + ((st * 64) + dt * 16 + fr) * 32 + fq * 8);
;             o[dt] = MFMA16(vf, pf, o[dt]);
;           }
amdhsa.kernels:
  - .agpr_count:     0
    .args:
      - .offset:         0
        .size:           168
        .value_kind:     by_value
      - .offset:         168
        .size:           4
        .value_kind:     hidden_block_count_x
      - .offset:         172
        .size:           4
        .value_kind:     hidden_block_count_y
      - .offset:         176
        .size:           4
        .value_kind:     hidden_block_count_z
      - .offset:         180
        .size:           2
        .value_kind:     hidden_group_size_x
      - .offset:         182
        .size:           2
        .value_kind:     hidden_group_size_y
      - .offset:         184
        .size:           2
        .value_kind:     hidden_group_size_z
      - .offset:         186
        .size:           2
        .value_kind:     hidden_remainder_x
      - .offset:         188
        .size:           2
        .value_kind:     hidden_remainder_y
      - .offset:         190
        .size:           2
        .value_kind:     hidden_remainder_z
      - .offset:         208
        .size:           8
        .value_kind:     hidden_global_offset_x
      - .offset:         216
        .size:           8
        .value_kind:     hidden_global_offset_y
      - .offset:         224
        .size:           8
        .value_kind:     hidden_global_offset_z
      - .offset:         232
        .size:           2
        .value_kind:     hidden_grid_dims
      - .offset:         256
        .size:           8
        .value_kind:     hidden_multigrid_sync_arg
      - .offset:         288
        .size:           4
        .value_kind:     hidden_dynamic_lds_size
    .group_segment_fixed_size: 24832
    .kernarg_segment_align: 8
    .kernarg_segment_size: 424
    .language:       OpenCL C
    .language_version:
      - 2
      - 0
    .max_flat_workgroup_size: 512
    .name:           _Z9hymba_fwd6Params
    .private_segment_fixed_size: 0
    .sgpr_count:     106
    .sgpr_spill_count: 267
    .symbol:         _Z9hymba_fwd6Params.kd
    .uniform_work_group_size: 1
    .uses_dynamic_stack: false
    .vgpr_count:     256
    .vgpr_spill_count: 0
    .wavefront_size: 64
